# attention: half the workgroups run one wave per SIMD and start at once (take the longest tasks), the other half run 8 waves and start ~2us later
# baseline (speedup 1.0000x reference)
; __device__ __forceinline__ void attn_phase(const Ctx& c, ArgsP a, int l, int ctr_slot) {
;     unsigned* ctr0 = (unsigned*)(c.ws + WS_CTL) + 64 * ctr_slot;
;     const int myq = (int)(__builtin_amdgcn_s_getreg((3 << 11) | 20) & 7u);
;     for (int qi = 0; qi < 8; ++qi) {
;         const int q = (myq + qi) & 7;
;         unsigned* ctr = ctr0 + 64 * q;
;         for (;;) {
;             int t = 0;
;             if (c.lane == 0) t = (int)atomicAdd(ctr, 1u);
;             t = __builtin_amdgcn_readfirstlane(t);
;             if (t >= 448) break;
;             Ctx ct = c; { int ln = c.lane; asm volatile("" : "+v"(ln)); ct.lane = ln; }
;             int ll = l; asm volatile("" : "+s"(ll));
.LBB0_119:
	s_and_b64 vcc, exec, s[4:5]
	s_cbranch_vccz .LBB0_332
	s_cmp_gt_i32 s2, 2
	s_mov_b64 s[4:5], -1
	s_cbranch_scc0 .LBB0_328
	s_add_u32 s3, s48, 0x25700000
	v_writelane_b32 v255, s3, 20
	s_addc_u32 s3, s49, 0
	v_writelane_b32 v255, s3, 21
	s_cmp_lt_i32 s2, 4
	s_cbranch_scc1 .LBB0_235
	s_cmp_gt_i32 s2, 4
	s_cbranch_scc0 .LBB0_220
	s_lshl_b32 s2, s67, 9
	s_ashr_i32 s3, s2, 31
	v_readlane_b32 s4, v254, 47
	s_add_u32 s2, s4, s2
	v_readlane_b32 s4, v254, 48
	s_addc_u32 s3, s4, s3
	s_lshl_b64 s[2:3], s[2:3], 2
	v_writelane_b32 v255, s67, 22
	s_add_u32 s2, s48, s2
	v_writelane_b32 v255, s2, 30
	s_addc_u32 s2, s49, s3
	v_writelane_b32 v255, s2, 31
	s_getreg_b32 s2, hwreg(HW_REG_XCC_ID, 0, 4)
	v_writelane_b32 v255, s2, 32
	s_add_u32 s2, s48, 0x2b400000
	v_writelane_b32 v255, s2, 26
	s_addc_u32 s2, s49, 0
	v_writelane_b32 v255, s2, 28
	s_add_u32 s2, s48, 0x2e900000
	v_writelane_b32 v255, s2, 23
	s_addc_u32 s2, s49, 0
	v_writelane_b32 v255, s2, 24
	v_readlane_b32 s2, v254, 62
	s_lshl_b32 s2, s2, 14
	s_add_i32 s52, s2, 0
	s_add_u32 s77, s48, 0x2dd00000
	s_addc_u32 s2, s49, 0
	s_add_u32 s3, s48, 0x2a700000
	s_addc_u32 s63, s49, 0
	s_add_u32 s88, s48, 0x2d500000
	s_addc_u32 s89, s49, 0
	s_add_u32 s51, s48, 0x2b500000
	s_mov_b32 s67, 0
	v_cmp_eq_u32_e64 s[6:7], 0, v198
	v_writelane_b32 v255, s2, 25
	s_addc_u32 s95, s49, 0
	v_readlane_b32 s4, v254, 62
	s_nop 3
	s_bitcmp1_b32 s76, 3
	s_cbranch_scc1 .Lattn_packed
	s_cmp_gt_u32 s4, 3
	s_cbranch_scc1 .LBB0_219
	s_branch .LBB0_125
.Lattn_packed:
	s_sleep 64
	s_branch .LBB0_125
